# v050 with the nt hint dropped from the 32 residual-stream LOADS of the two residual epilogues (stores keep nt)
# baseline (speedup 1.0000x reference)
.LBB0_628:
	s_ashr_i32 s23, s22, 31
	s_lshl_b64 s[34:35], s[22:23], 20
	s_add_u32 s36, s50, s34
	v_lshl_add_u32 v0, v130, 1, v214
	s_addc_u32 s37, s51, s35
	v_lshl_add_u64 v[210:211], s[36:37], 0, v[0:1]
	v_add_co_u32_e32 v132, vcc, s73, v210
	global_load_dwordx4 v[230:233], v0, s[36:37]
	global_load_dwordx4 v[170:173], v0, s[36:37] offset:256
	s_mov_b64 s[62:63], 0x10000
	v_addc_co_u32_e32 v133, vcc, 0, v211, vcc
	v_lshl_add_u64 v[130:131], v[210:211], 0, s[62:63]
	global_load_dwordx4 v[166:169], v[132:133], off
	global_load_dwordx4 v[162:165], v[130:131], off offset:256
	v_add_co_u32_e32 v132, vcc, s79, v210
	s_mov_b64 s[62:63], 0x20000
	s_nop 0
	v_addc_co_u32_e32 v133, vcc, 0, v211, vcc
	s_mov_b32 s21, 0x30000
	v_lshl_add_u64 v[130:131], v[210:211], 0, s[62:63]
	global_load_dwordx4 v[158:161], v[132:133], off
	global_load_dwordx4 v[146:149], v[130:131], off offset:256
	s_mov_b64 s[62:63], 0x30000
	v_add_co_u32_e32 v132, vcc, s21, v210
	v_lshl_add_u64 v[130:131], v[210:211], 0, s[62:63]
	s_nop 0
	v_addc_co_u32_e32 v133, vcc, 0, v211, vcc
	global_load_dwordx4 v[142:145], v[132:133], off
	s_nop 0
	global_load_dwordx4 v[130:133], v[130:131], off offset:256
	s_add_u32 s34, s46, s34
	s_addc_u32 s35, s47, s35
	v_lshl_add_u64 v[208:209], s[34:35], 0, v[0:1]
	s_and_b64 vcc, exec, s[8:9]
	s_waitcnt vmcnt(0)
	v_cvt_f32_f16_e32 v220, v230
	v_cvt_f32_f16_sdwa v221, v230 dst_sel:DWORD dst_unused:UNUSED_PAD src0_sel:WORD_1
	v_cvt_f32_f16_e32 v230, v231
	v_cvt_f32_f16_sdwa v231, v231 dst_sel:DWORD dst_unused:UNUSED_PAD src0_sel:WORD_1
	v_cvt_f32_f16_e32 v234, v232
	v_cvt_f32_f16_e32 v236, v233
	v_cvt_f32_f16_sdwa v237, v233 dst_sel:DWORD dst_unused:UNUSED_PAD src0_sel:WORD_1
	v_cvt_f32_f16_sdwa v235, v232 dst_sel:DWORD dst_unused:UNUSED_PAD src0_sel:WORD_1
	v_pk_fma_f32 v[156:157], v[156:157], v[72:73], v[230:231]
	v_pk_fma_f32 v[154:155], v[154:155], v[70:71], v[220:221]
	v_pk_fma_f32 v[152:153], v[152:153], v[80:81], v[236:237]
	v_pk_fma_f32 v[150:151], v[150:151], v[78:79], v[234:235]
	v_cvt_pk_f16_f32 v230, v154, v155
	v_cvt_pk_f16_f32 v231, v156, v157
	v_cvt_pk_f16_f32 v232, v150, v151
	v_cvt_pk_f16_f32 v233, v152, v153
	global_store_dwordx4 v0, v[230:233], s[36:37] nt
	s_cbranch_vccnz .LBB0_630
	s_nop 0
	v_pk_mul_f32 v[230:231], v[200:201], v[154:155]
	v_pk_mul_f32 v[232:233], v[198:199], v[150:151]
	v_pk_mul_f32 v[220:221], v[204:205], v[156:157]
	v_pk_mul_f32 v[234:235], v[206:207], v[152:153]
	v_cvt_pk_bf16_f32 v230, v230, v231
	v_cvt_pk_bf16_f32 v231, v220, v221
	v_cvt_pk_bf16_f32 v232, v232, v233
	s_nop 0
	v_cvt_pk_bf16_f32 v233, v234, v235
	global_store_dwordx4 v[208:209], v[230:233], off

.LBB0_632:
	v_mul_f32_e32 v0, v155, v155
	v_mul_f32_e32 v151, v151, v151
	v_mul_f32_e32 v127, v127, v127
	v_mul_f32_e32 v115, v115, v115
	v_fmac_f32_e32 v0, v154, v154
	v_mul_f32_e32 v154, v157, v157
	v_fmac_f32_e32 v151, v150, v150
	v_mul_f32_e32 v150, v153, v153
	v_fmac_f32_e32 v127, v126, v126
	v_mul_f32_e32 v126, v129, v129
	v_fmac_f32_e32 v115, v114, v114
	v_mul_f32_e32 v114, v117, v117
	v_fmac_f32_e32 v154, v156, v156
	v_fmac_f32_e32 v150, v152, v152
	v_fmac_f32_e32 v126, v128, v128
	v_fmac_f32_e32 v114, v116, v116
	v_add_f32_e32 v0, v0, v154
	v_add_f32_e32 v150, v151, v150
	v_add_f32_e32 v126, v127, v126
	v_add_f32_e32 v114, v115, v114
	v_add_f32_e32 v0, v0, v150
	v_add_f32_e32 v114, v126, v114
	s_mov_b64 s[34:35], 0x80000
	v_add_co_u32_e32 v116, vcc, 0x80000, v210
	v_add_f32_e32 v0, v0, v114
	v_lshl_add_u64 v[114:115], v[210:211], 0, s[34:35]
	v_addc_co_u32_e32 v117, vcc, 0, v211, vcc
	global_load_dwordx4 v[126:129], v[116:117], off
	s_nop 0
	global_load_dwordx4 v[114:117], v[114:115], off offset:256
	v_mov_b32_e32 v150, v0
	s_nop 1
	v_permlane16_swap_b32 v0, v150
	s_nop 0
	v_add_f32_e32 v0, v0, v150
	v_mov_b32_e32 v150, v0
	s_nop 1
	v_permlane32_swap_b32 v150, v0
	s_and_saveexec_b64 s[34:35], s[10:11]
	v_add_f32_e32 v0, v150, v0
	ds_write_b32 v228, v0
	s_or_b64 exec, exec, s[34:35]
	v_cvt_f32_f16_sdwa v155, v168 dst_sel:DWORD dst_unused:UNUSED_PAD src0_sel:WORD_1
	v_cvt_f32_f16_e32 v154, v168
	v_cvt_f32_f16_sdwa v151, v166 dst_sel:DWORD dst_unused:UNUSED_PAD src0_sel:WORD_1
	v_cvt_f32_f16_e32 v150, v166
	v_cvt_f32_f16_sdwa v153, v167 dst_sel:DWORD dst_unused:UNUSED_PAD src0_sel:WORD_1
	v_cvt_f32_f16_e32 v152, v167
	v_cvt_f32_f16_sdwa v157, v169 dst_sel:DWORD dst_unused:UNUSED_PAD src0_sel:WORD_1
	v_cvt_f32_f16_e32 v156, v169
	v_pk_fma_f32 v[134:135], v[134:135], v[78:79], v[154:155]
	v_add_co_u32_e32 v154, vcc, 0x10000, v210
	v_pk_fma_f32 v[140:141], v[140:141], v[72:73], v[152:153]
	v_pk_fma_f32 v[138:139], v[138:139], v[70:71], v[150:151]
	v_pk_fma_f32 v[136:137], v[136:137], v[80:81], v[156:157]
	v_addc_co_u32_e32 v155, vcc, 0, v211, vcc
	v_cvt_pk_f16_f32 v150, v138, v139
	v_cvt_pk_f16_f32 v151, v140, v141
	v_cvt_pk_f16_f32 v152, v134, v135
	v_cvt_pk_f16_f32 v153, v136, v137
	s_and_b64 vcc, exec, s[8:9]
	global_store_dwordx4 v[154:155], v[150:153], off nt
	s_cbranch_vccnz .LBB0_636
	s_nop 0
	v_pk_mul_f32 v[152:153], v[204:205], v[140:141]
	v_pk_mul_f32 v[150:151], v[200:201], v[138:139]
	v_pk_mul_f32 v[154:155], v[206:207], v[136:137]
	v_pk_mul_f32 v[156:157], v[198:199], v[134:135]
	v_cvt_pk_bf16_f32 v150, v150, v151
	v_cvt_pk_bf16_f32 v151, v152, v153
	s_nop 0
	v_cvt_pk_bf16_f32 v152, v156, v157
	v_cvt_pk_bf16_f32 v153, v154, v155
	v_add_co_u32_e32 v154, vcc, 0x10000, v208
	s_nop 1
	v_addc_co_u32_e32 v155, vcc, 0, v209, vcc
	global_store_dwordx4 v[154:155], v[150:153], off

.LBB0_638:
	v_mul_f32_e32 v0, v139, v139
	v_mul_f32_e32 v135, v135, v135
	v_mul_f32_e32 v123, v123, v123
	v_mul_f32_e32 v119, v119, v119
	v_fmac_f32_e32 v0, v138, v138
	v_mul_f32_e32 v138, v141, v141
	v_fmac_f32_e32 v135, v134, v134
	v_mul_f32_e32 v134, v137, v137
	v_fmac_f32_e32 v123, v122, v122
	v_mul_f32_e32 v122, v125, v125
	v_fmac_f32_e32 v119, v118, v118
	v_mul_f32_e32 v118, v121, v121
	v_fmac_f32_e32 v138, v140, v140
	v_fmac_f32_e32 v134, v136, v136
	v_fmac_f32_e32 v122, v124, v124
	v_fmac_f32_e32 v118, v120, v120
	v_add_f32_e32 v0, v0, v138
	v_add_f32_e32 v134, v135, v134
	v_add_f32_e32 v122, v123, v122
	v_add_f32_e32 v118, v119, v118
	v_add_f32_e32 v0, v0, v134
	v_add_f32_e32 v118, v122, v118
	s_mov_b64 s[34:35], 0x90000
	v_add_co_u32_e32 v120, vcc, 0x90000, v210
	v_add_f32_e32 v0, v0, v118
	v_lshl_add_u64 v[118:119], v[210:211], 0, s[34:35]
	v_addc_co_u32_e32 v121, vcc, 0, v211, vcc
	global_load_dwordx4 v[122:125], v[120:121], off
	s_nop 0
	global_load_dwordx4 v[118:121], v[118:119], off offset:256
	v_mov_b32_e32 v134, v0
	s_nop 1
	v_permlane16_swap_b32 v0, v134
	s_nop 0
	v_add_f32_e32 v0, v0, v134
	v_mov_b32_e32 v134, v0
	s_nop 1
	v_permlane32_swap_b32 v134, v0
	s_and_saveexec_b64 s[34:35], s[10:11]
	v_add_f32_e32 v0, v134, v0
	ds_write_b32 v228, v0 offset:256
	s_or_b64 exec, exec, s[34:35]
	v_cvt_f32_f16_sdwa v139, v160 dst_sel:DWORD dst_unused:UNUSED_PAD src0_sel:WORD_1
	v_cvt_f32_f16_e32 v138, v160
	v_cvt_f32_f16_sdwa v135, v158 dst_sel:DWORD dst_unused:UNUSED_PAD src0_sel:WORD_1
	v_cvt_f32_f16_e32 v134, v158
	v_cvt_f32_f16_sdwa v137, v159 dst_sel:DWORD dst_unused:UNUSED_PAD src0_sel:WORD_1
	v_cvt_f32_f16_e32 v136, v159
	v_cvt_f32_f16_sdwa v141, v161 dst_sel:DWORD dst_unused:UNUSED_PAD src0_sel:WORD_1
	v_cvt_f32_f16_e32 v140, v161
	v_pk_fma_f32 v[106:107], v[106:107], v[78:79], v[138:139]
	v_add_co_u32_e32 v138, vcc, 0x20000, v210
	v_pk_fma_f32 v[112:113], v[112:113], v[72:73], v[136:137]
	v_pk_fma_f32 v[110:111], v[110:111], v[70:71], v[134:135]
	v_pk_fma_f32 v[108:109], v[108:109], v[80:81], v[140:141]
	v_addc_co_u32_e32 v139, vcc, 0, v211, vcc
	v_cvt_pk_f16_f32 v134, v110, v111
	v_cvt_pk_f16_f32 v135, v112, v113
	v_cvt_pk_f16_f32 v136, v106, v107
	v_cvt_pk_f16_f32 v137, v108, v109
	s_and_b64 vcc, exec, s[8:9]
	global_store_dwordx4 v[138:139], v[134:137], off nt
	s_cbranch_vccnz .LBB0_642
	s_nop 0
	v_pk_mul_f32 v[136:137], v[204:205], v[112:113]
	v_pk_mul_f32 v[134:135], v[200:201], v[110:111]
	v_pk_mul_f32 v[138:139], v[206:207], v[108:109]
	v_pk_mul_f32 v[140:141], v[198:199], v[106:107]
	v_cvt_pk_bf16_f32 v134, v134, v135
	v_cvt_pk_bf16_f32 v135, v136, v137
	s_nop 0
	v_cvt_pk_bf16_f32 v136, v140, v141
	v_cvt_pk_bf16_f32 v137, v138, v139
	v_add_co_u32_e32 v138, vcc, 0x20000, v208
	s_nop 1
	v_addc_co_u32_e32 v139, vcc, 0, v209, vcc
	global_store_dwordx4 v[138:139], v[134:137], off

.LBB0_644:
	v_mul_f32_e32 v0, v111, v111
	v_mul_f32_e32 v107, v107, v107
	v_mul_f32_e32 v103, v103, v103
	v_mul_f32_e32 v99, v99, v99
	v_fmac_f32_e32 v0, v110, v110
	v_mul_f32_e32 v110, v113, v113
	v_fmac_f32_e32 v107, v106, v106
	v_mul_f32_e32 v106, v109, v109
	v_fmac_f32_e32 v103, v102, v102
	v_mul_f32_e32 v102, v105, v105
	v_fmac_f32_e32 v99, v98, v98
	v_mul_f32_e32 v98, v101, v101
	v_fmac_f32_e32 v110, v112, v112
	v_fmac_f32_e32 v106, v108, v108
	v_fmac_f32_e32 v102, v104, v104
	v_fmac_f32_e32 v98, v100, v100
	v_add_f32_e32 v0, v0, v110
	v_add_f32_e32 v106, v107, v106
	v_add_f32_e32 v102, v103, v102
	v_add_f32_e32 v98, v99, v98
	v_add_f32_e32 v0, v0, v106
	v_add_f32_e32 v98, v102, v98
	s_mov_b64 s[34:35], 0xa0000
	v_add_co_u32_e32 v100, vcc, 0xa0000, v210
	v_add_f32_e32 v0, v0, v98
	v_lshl_add_u64 v[98:99], v[210:211], 0, s[34:35]
	v_addc_co_u32_e32 v101, vcc, 0, v211, vcc
	global_load_dwordx4 v[102:105], v[100:101], off
	s_nop 0
	global_load_dwordx4 v[98:101], v[98:99], off offset:256
	v_mov_b32_e32 v106, v0
	s_nop 1
	v_permlane16_swap_b32 v106, v0
	s_nop 0
	v_add_f32_e32 v0, v106, v0
	v_mov_b32_e32 v106, v0
	s_nop 1
	v_permlane32_swap_b32 v106, v0
	s_and_saveexec_b64 s[34:35], s[10:11]
	v_add_f32_e32 v0, v106, v0
	ds_write_b32 v228, v0 offset:512
	s_or_b64 exec, exec, s[34:35]
	v_cvt_f32_f16_sdwa v111, v144 dst_sel:DWORD dst_unused:UNUSED_PAD src0_sel:WORD_1
	v_cvt_f32_f16_e32 v110, v144
	v_cvt_f32_f16_sdwa v107, v142 dst_sel:DWORD dst_unused:UNUSED_PAD src0_sel:WORD_1
	v_cvt_f32_f16_e32 v106, v142
	v_cvt_f32_f16_sdwa v109, v143 dst_sel:DWORD dst_unused:UNUSED_PAD src0_sel:WORD_1
	v_cvt_f32_f16_e32 v108, v143
	v_cvt_f32_f16_sdwa v113, v145 dst_sel:DWORD dst_unused:UNUSED_PAD src0_sel:WORD_1
	v_cvt_f32_f16_e32 v112, v145
	v_pk_fma_f32 v[90:91], v[90:91], v[78:79], v[110:111]
	v_add_co_u32_e32 v110, vcc, 0x30000, v210
	v_pk_fma_f32 v[96:97], v[96:97], v[72:73], v[108:109]
	v_pk_fma_f32 v[94:95], v[94:95], v[70:71], v[106:107]
	v_pk_fma_f32 v[92:93], v[92:93], v[80:81], v[112:113]
	v_addc_co_u32_e32 v111, vcc, 0, v211, vcc
	v_cvt_pk_f16_f32 v106, v94, v95
	v_cvt_pk_f16_f32 v107, v96, v97
	v_cvt_pk_f16_f32 v108, v90, v91
	v_cvt_pk_f16_f32 v109, v92, v93
	s_and_b64 vcc, exec, s[8:9]
	global_store_dwordx4 v[110:111], v[106:109], off nt
	s_cbranch_vccnz .LBB0_648
	s_nop 0
	v_pk_mul_f32 v[108:109], v[204:205], v[96:97]
	v_pk_mul_f32 v[106:107], v[200:201], v[94:95]
	v_pk_mul_f32 v[110:111], v[206:207], v[92:93]
	v_pk_mul_f32 v[112:113], v[198:199], v[90:91]
	v_cvt_pk_bf16_f32 v106, v106, v107
	v_cvt_pk_bf16_f32 v107, v108, v109
	s_nop 0
	v_cvt_pk_bf16_f32 v108, v112, v113
	v_cvt_pk_bf16_f32 v109, v110, v111
	v_add_co_u32_e32 v110, vcc, 0x30000, v208
	s_nop 1
	v_addc_co_u32_e32 v111, vcc, 0, v209, vcc
	global_store_dwordx4 v[110:111], v[106:109], off

.LBB0_650:
	v_mul_f32_e32 v0, v95, v95
	v_mul_f32_e32 v91, v91, v91
	v_mul_f32_e32 v87, v87, v87
	v_mul_f32_e32 v83, v83, v83
	v_fmac_f32_e32 v0, v94, v94
	v_mul_f32_e32 v94, v97, v97
	v_fmac_f32_e32 v91, v90, v90
	v_mul_f32_e32 v90, v93, v93
	v_fmac_f32_e32 v87, v86, v86
	v_mul_f32_e32 v86, v89, v89
	v_fmac_f32_e32 v83, v82, v82
	v_mul_f32_e32 v82, v85, v85
	v_fmac_f32_e32 v94, v96, v96
	v_fmac_f32_e32 v90, v92, v92
	v_fmac_f32_e32 v86, v88, v88
	v_fmac_f32_e32 v82, v84, v84
	v_add_f32_e32 v0, v0, v94
	v_add_f32_e32 v90, v91, v90
	v_add_f32_e32 v86, v87, v86
	v_add_f32_e32 v82, v83, v82
	v_add_f32_e32 v0, v0, v90
	v_add_f32_e32 v82, v86, v82
	s_mov_b64 s[34:35], 0xb0000
	v_add_co_u32_e32 v84, vcc, 0xb0000, v210
	v_add_f32_e32 v0, v0, v82
	v_lshl_add_u64 v[82:83], v[210:211], 0, s[34:35]
	v_addc_co_u32_e32 v85, vcc, 0, v211, vcc
	global_load_dwordx4 v[86:89], v[84:85], off
	s_nop 0
	global_load_dwordx4 v[82:85], v[82:83], off offset:256
	v_mov_b32_e32 v90, v0
	s_nop 1
	v_permlane16_swap_b32 v90, v0
	s_nop 0
	v_add_f32_e32 v0, v90, v0
	v_mov_b32_e32 v90, v0
	s_nop 1
	v_permlane32_swap_b32 v90, v0
	s_and_saveexec_b64 s[34:35], s[10:11]
	v_add_f32_e32 v0, v90, v0
	ds_write_b32 v228, v0 offset:768
	s_or_b64 exec, exec, s[34:35]
	s_waitcnt vmcnt(13)
	v_cvt_f32_f16_sdwa v95, v128 dst_sel:DWORD dst_unused:UNUSED_PAD src0_sel:WORD_1
	v_cvt_f32_f16_e32 v94, v128
	v_cvt_f32_f16_sdwa v91, v126 dst_sel:DWORD dst_unused:UNUSED_PAD src0_sel:WORD_1
	v_cvt_f32_f16_e32 v90, v126
	v_cvt_f32_f16_sdwa v93, v127 dst_sel:DWORD dst_unused:UNUSED_PAD src0_sel:WORD_1
	v_cvt_f32_f16_e32 v92, v127
	v_cvt_f32_f16_sdwa v97, v129 dst_sel:DWORD dst_unused:UNUSED_PAD src0_sel:WORD_1
	v_cvt_f32_f16_e32 v96, v129
	v_pk_fma_f32 v[58:59], v[58:59], v[78:79], v[94:95]
	v_add_co_u32_e32 v94, vcc, 0x80000, v210
	v_pk_fma_f32 v[64:65], v[64:65], v[72:73], v[92:93]
	v_pk_fma_f32 v[62:63], v[62:63], v[70:71], v[90:91]
	v_pk_fma_f32 v[60:61], v[60:61], v[80:81], v[96:97]
	v_addc_co_u32_e32 v95, vcc, 0, v211, vcc
	v_cvt_pk_f16_f32 v90, v62, v63
	v_cvt_pk_f16_f32 v91, v64, v65
	v_cvt_pk_f16_f32 v92, v58, v59
	v_cvt_pk_f16_f32 v93, v60, v61
	s_and_b64 vcc, exec, s[8:9]
	global_store_dwordx4 v[94:95], v[90:93], off nt
	s_cbranch_vccnz .LBB0_654
	s_nop 0
	v_pk_mul_f32 v[92:93], v[204:205], v[64:65]
	v_pk_mul_f32 v[90:91], v[200:201], v[62:63]
	v_pk_mul_f32 v[94:95], v[206:207], v[60:61]
	v_pk_mul_f32 v[96:97], v[198:199], v[58:59]
	v_cvt_pk_bf16_f32 v90, v90, v91
	v_cvt_pk_bf16_f32 v91, v92, v93
	s_nop 0
	v_cvt_pk_bf16_f32 v92, v96, v97
	v_cvt_pk_bf16_f32 v93, v94, v95
	v_add_co_u32_e32 v94, vcc, 0x80000, v208
	s_nop 1
	v_addc_co_u32_e32 v95, vcc, 0, v209, vcc
	global_store_dwordx4 v[94:95], v[90:93], off

.LBB0_916:
	s_ashr_i32 s21, s20, 31
	s_lshl_b64 s[26:27], s[20:21], 20
	s_add_u32 s28, s45, s26
	v_lshl_add_u32 v0, v130, 1, v214
	s_addc_u32 s29, s46, s27
	v_lshl_add_u64 v[210:211], s[28:29], 0, v[0:1]
	v_add_co_u32_e32 v132, vcc, s95, v210
	global_load_dwordx4 v[230:233], v0, s[28:29]
	global_load_dwordx4 v[170:173], v0, s[28:29] offset:256
	s_mov_b64 s[30:31], 0x10000
	v_addc_co_u32_e32 v133, vcc, 0, v211, vcc
	v_lshl_add_u64 v[130:131], v[210:211], 0, s[30:31]
	global_load_dwordx4 v[166:169], v[132:133], off
	global_load_dwordx4 v[162:165], v[130:131], off offset:256
	v_add_co_u32_e32 v132, vcc, s79, v210
	s_mov_b64 s[30:31], 0x20000
	s_nop 0
	v_addc_co_u32_e32 v133, vcc, 0, v211, vcc
	s_mov_b32 s19, 0x30000
	v_lshl_add_u64 v[130:131], v[210:211], 0, s[30:31]
	global_load_dwordx4 v[158:161], v[132:133], off
	global_load_dwordx4 v[146:149], v[130:131], off offset:256
	s_mov_b64 s[30:31], 0x30000
	v_add_co_u32_e32 v132, vcc, s19, v210
	v_lshl_add_u64 v[130:131], v[210:211], 0, s[30:31]
	s_nop 0
	v_addc_co_u32_e32 v133, vcc, 0, v211, vcc
	global_load_dwordx4 v[142:145], v[132:133], off
	s_nop 0
	global_load_dwordx4 v[130:133], v[130:131], off offset:256
	s_add_u32 s26, s43, s26
	s_addc_u32 s27, s44, s27
	v_lshl_add_u64 v[208:209], s[26:27], 0, v[0:1]
	s_and_b64 vcc, exec, s[8:9]
	s_waitcnt vmcnt(0)
	v_cvt_f32_f16_e32 v220, v230
	v_cvt_f32_f16_sdwa v221, v230 dst_sel:DWORD dst_unused:UNUSED_PAD src0_sel:WORD_1
	v_cvt_f32_f16_e32 v230, v231
	v_cvt_f32_f16_sdwa v231, v231 dst_sel:DWORD dst_unused:UNUSED_PAD src0_sel:WORD_1
	v_cvt_f32_f16_e32 v234, v232
	v_cvt_f32_f16_e32 v236, v233
	v_cvt_f32_f16_sdwa v237, v233 dst_sel:DWORD dst_unused:UNUSED_PAD src0_sel:WORD_1
	v_cvt_f32_f16_sdwa v235, v232 dst_sel:DWORD dst_unused:UNUSED_PAD src0_sel:WORD_1
	v_pk_fma_f32 v[156:157], v[156:157], v[72:73], v[230:231]
	v_pk_fma_f32 v[154:155], v[154:155], v[70:71], v[220:221]
	v_pk_fma_f32 v[152:153], v[152:153], v[80:81], v[236:237]
	v_pk_fma_f32 v[150:151], v[150:151], v[78:79], v[234:235]
	v_cvt_pk_f16_f32 v230, v154, v155
	v_cvt_pk_f16_f32 v231, v156, v157
	v_cvt_pk_f16_f32 v232, v150, v151
	v_cvt_pk_f16_f32 v233, v152, v153
	global_store_dwordx4 v0, v[230:233], s[28:29] nt
	s_cbranch_vccnz .LBB0_918
	s_nop 0
	v_pk_mul_f32 v[230:231], v[200:201], v[154:155]
	v_pk_mul_f32 v[232:233], v[198:199], v[150:151]
	v_pk_mul_f32 v[220:221], v[204:205], v[156:157]
	v_pk_mul_f32 v[234:235], v[206:207], v[152:153]
	v_cvt_pk_bf16_f32 v230, v230, v231
	v_cvt_pk_bf16_f32 v231, v220, v221
	v_cvt_pk_bf16_f32 v232, v232, v233
	s_nop 0
	v_cvt_pk_bf16_f32 v233, v234, v235
	global_store_dwordx4 v[208:209], v[230:233], off

.LBB0_920:
	v_mul_f32_e32 v0, v155, v155
	v_mul_f32_e32 v151, v151, v151
	v_mul_f32_e32 v127, v127, v127
	v_mul_f32_e32 v115, v115, v115
	v_fmac_f32_e32 v0, v154, v154
	v_mul_f32_e32 v154, v157, v157
	v_fmac_f32_e32 v151, v150, v150
	v_mul_f32_e32 v150, v153, v153
	v_fmac_f32_e32 v127, v126, v126
	v_mul_f32_e32 v126, v129, v129
	v_fmac_f32_e32 v115, v114, v114
	v_mul_f32_e32 v114, v117, v117
	v_fmac_f32_e32 v154, v156, v156
	v_fmac_f32_e32 v150, v152, v152
	v_fmac_f32_e32 v126, v128, v128
	v_fmac_f32_e32 v114, v116, v116
	v_add_f32_e32 v0, v0, v154
	v_add_f32_e32 v150, v151, v150
	v_add_f32_e32 v126, v127, v126
	v_add_f32_e32 v114, v115, v114
	v_add_f32_e32 v0, v0, v150
	v_add_f32_e32 v114, v126, v114
	s_mov_b64 s[26:27], 0x80000
	v_add_co_u32_e32 v116, vcc, 0x80000, v210
	v_add_f32_e32 v0, v0, v114
	v_lshl_add_u64 v[114:115], v[210:211], 0, s[26:27]
	v_addc_co_u32_e32 v117, vcc, 0, v211, vcc
	global_load_dwordx4 v[126:129], v[116:117], off
	s_nop 0
	global_load_dwordx4 v[114:117], v[114:115], off offset:256
	v_mov_b32_e32 v150, v0
	s_nop 1
	v_permlane16_swap_b32 v0, v150
	s_nop 0
	v_add_f32_e32 v0, v0, v150
	v_mov_b32_e32 v150, v0
	s_nop 1
	v_permlane32_swap_b32 v150, v0
	s_and_saveexec_b64 s[26:27], s[10:11]
	v_add_f32_e32 v0, v150, v0
	ds_write_b32 v228, v0
	s_or_b64 exec, exec, s[26:27]
	v_cvt_f32_f16_sdwa v155, v168 dst_sel:DWORD dst_unused:UNUSED_PAD src0_sel:WORD_1
	v_cvt_f32_f16_e32 v154, v168
	v_cvt_f32_f16_sdwa v151, v166 dst_sel:DWORD dst_unused:UNUSED_PAD src0_sel:WORD_1
	v_cvt_f32_f16_e32 v150, v166
	v_cvt_f32_f16_sdwa v153, v167 dst_sel:DWORD dst_unused:UNUSED_PAD src0_sel:WORD_1
	v_cvt_f32_f16_e32 v152, v167
	v_cvt_f32_f16_sdwa v157, v169 dst_sel:DWORD dst_unused:UNUSED_PAD src0_sel:WORD_1
	v_cvt_f32_f16_e32 v156, v169
	v_pk_fma_f32 v[134:135], v[134:135], v[78:79], v[154:155]
	v_add_co_u32_e32 v154, vcc, 0x10000, v210
	v_pk_fma_f32 v[140:141], v[140:141], v[72:73], v[152:153]
	v_pk_fma_f32 v[138:139], v[138:139], v[70:71], v[150:151]
	v_pk_fma_f32 v[136:137], v[136:137], v[80:81], v[156:157]
	v_addc_co_u32_e32 v155, vcc, 0, v211, vcc
	v_cvt_pk_f16_f32 v150, v138, v139
	v_cvt_pk_f16_f32 v151, v140, v141
	v_cvt_pk_f16_f32 v152, v134, v135
	v_cvt_pk_f16_f32 v153, v136, v137
	s_and_b64 vcc, exec, s[8:9]
	global_store_dwordx4 v[154:155], v[150:153], off nt
	s_cbranch_vccnz .LBB0_924
	s_nop 0
	v_pk_mul_f32 v[152:153], v[204:205], v[140:141]
	v_pk_mul_f32 v[150:151], v[200:201], v[138:139]
	v_pk_mul_f32 v[154:155], v[206:207], v[136:137]
	v_pk_mul_f32 v[156:157], v[198:199], v[134:135]
	v_cvt_pk_bf16_f32 v150, v150, v151
	v_cvt_pk_bf16_f32 v151, v152, v153
	s_nop 0
	v_cvt_pk_bf16_f32 v152, v156, v157
	v_cvt_pk_bf16_f32 v153, v154, v155
	v_add_co_u32_e32 v154, vcc, 0x10000, v208
	s_nop 1
	v_addc_co_u32_e32 v155, vcc, 0, v209, vcc
	global_store_dwordx4 v[154:155], v[150:153], off

.LBB0_926:
	v_mul_f32_e32 v0, v139, v139
	v_mul_f32_e32 v135, v135, v135
	v_mul_f32_e32 v123, v123, v123
	v_mul_f32_e32 v119, v119, v119
	v_fmac_f32_e32 v0, v138, v138
	v_mul_f32_e32 v138, v141, v141
	v_fmac_f32_e32 v135, v134, v134
	v_mul_f32_e32 v134, v137, v137
	v_fmac_f32_e32 v123, v122, v122
	v_mul_f32_e32 v122, v125, v125
	v_fmac_f32_e32 v119, v118, v118
	v_mul_f32_e32 v118, v121, v121
	v_fmac_f32_e32 v138, v140, v140
	v_fmac_f32_e32 v134, v136, v136
	v_fmac_f32_e32 v122, v124, v124
	v_fmac_f32_e32 v118, v120, v120
	v_add_f32_e32 v0, v0, v138
	v_add_f32_e32 v134, v135, v134
	v_add_f32_e32 v122, v123, v122
	v_add_f32_e32 v118, v119, v118
	v_add_f32_e32 v0, v0, v134
	v_add_f32_e32 v118, v122, v118
	s_mov_b64 s[26:27], 0x90000
	v_add_co_u32_e32 v120, vcc, 0x90000, v210
	v_add_f32_e32 v0, v0, v118
	v_lshl_add_u64 v[118:119], v[210:211], 0, s[26:27]
	v_addc_co_u32_e32 v121, vcc, 0, v211, vcc
	global_load_dwordx4 v[122:125], v[120:121], off
	s_nop 0
	global_load_dwordx4 v[118:121], v[118:119], off offset:256
	v_mov_b32_e32 v134, v0
	s_nop 1
	v_permlane16_swap_b32 v0, v134
	s_nop 0
	v_add_f32_e32 v0, v0, v134
	v_mov_b32_e32 v134, v0
	s_nop 1
	v_permlane32_swap_b32 v134, v0
	s_and_saveexec_b64 s[26:27], s[10:11]
	v_add_f32_e32 v0, v134, v0
	ds_write_b32 v228, v0 offset:256
	s_or_b64 exec, exec, s[26:27]
	v_cvt_f32_f16_sdwa v139, v160 dst_sel:DWORD dst_unused:UNUSED_PAD src0_sel:WORD_1
	v_cvt_f32_f16_e32 v138, v160
	v_cvt_f32_f16_sdwa v135, v158 dst_sel:DWORD dst_unused:UNUSED_PAD src0_sel:WORD_1
	v_cvt_f32_f16_e32 v134, v158
	v_cvt_f32_f16_sdwa v137, v159 dst_sel:DWORD dst_unused:UNUSED_PAD src0_sel:WORD_1
	v_cvt_f32_f16_e32 v136, v159
	v_cvt_f32_f16_sdwa v141, v161 dst_sel:DWORD dst_unused:UNUSED_PAD src0_sel:WORD_1
	v_cvt_f32_f16_e32 v140, v161
	v_pk_fma_f32 v[106:107], v[106:107], v[78:79], v[138:139]
	v_add_co_u32_e32 v138, vcc, 0x20000, v210
	v_pk_fma_f32 v[112:113], v[112:113], v[72:73], v[136:137]
	v_pk_fma_f32 v[110:111], v[110:111], v[70:71], v[134:135]
	v_pk_fma_f32 v[108:109], v[108:109], v[80:81], v[140:141]
	v_addc_co_u32_e32 v139, vcc, 0, v211, vcc
	v_cvt_pk_f16_f32 v134, v110, v111
	v_cvt_pk_f16_f32 v135, v112, v113
	v_cvt_pk_f16_f32 v136, v106, v107
	v_cvt_pk_f16_f32 v137, v108, v109
	s_and_b64 vcc, exec, s[8:9]
	global_store_dwordx4 v[138:139], v[134:137], off nt
	s_cbranch_vccnz .LBB0_930
	s_nop 0
	v_pk_mul_f32 v[136:137], v[204:205], v[112:113]
	v_pk_mul_f32 v[134:135], v[200:201], v[110:111]
	v_pk_mul_f32 v[138:139], v[206:207], v[108:109]
	v_pk_mul_f32 v[140:141], v[198:199], v[106:107]
	v_cvt_pk_bf16_f32 v134, v134, v135
	v_cvt_pk_bf16_f32 v135, v136, v137
	s_nop 0
	v_cvt_pk_bf16_f32 v136, v140, v141
	v_cvt_pk_bf16_f32 v137, v138, v139
	v_add_co_u32_e32 v138, vcc, 0x20000, v208
	s_nop 1
	v_addc_co_u32_e32 v139, vcc, 0, v209, vcc
	global_store_dwordx4 v[138:139], v[134:137], off

.LBB0_932:
	v_mul_f32_e32 v0, v111, v111
	v_mul_f32_e32 v107, v107, v107
	v_mul_f32_e32 v103, v103, v103
	v_mul_f32_e32 v99, v99, v99
	v_fmac_f32_e32 v0, v110, v110
	v_mul_f32_e32 v110, v113, v113
	v_fmac_f32_e32 v107, v106, v106
	v_mul_f32_e32 v106, v109, v109
	v_fmac_f32_e32 v103, v102, v102
	v_mul_f32_e32 v102, v105, v105
	v_fmac_f32_e32 v99, v98, v98
	v_mul_f32_e32 v98, v101, v101
	v_fmac_f32_e32 v110, v112, v112
	v_fmac_f32_e32 v106, v108, v108
	v_fmac_f32_e32 v102, v104, v104
	v_fmac_f32_e32 v98, v100, v100
	v_add_f32_e32 v0, v0, v110
	v_add_f32_e32 v106, v107, v106
	v_add_f32_e32 v102, v103, v102
	v_add_f32_e32 v98, v99, v98
	v_add_f32_e32 v0, v0, v106
	v_add_f32_e32 v98, v102, v98
	s_mov_b64 s[26:27], 0xa0000
	v_add_co_u32_e32 v100, vcc, 0xa0000, v210
	v_add_f32_e32 v0, v0, v98
	v_lshl_add_u64 v[98:99], v[210:211], 0, s[26:27]
	v_addc_co_u32_e32 v101, vcc, 0, v211, vcc
	global_load_dwordx4 v[102:105], v[100:101], off
	s_nop 0
	global_load_dwordx4 v[98:101], v[98:99], off offset:256
	v_mov_b32_e32 v106, v0
	s_nop 1
	v_permlane16_swap_b32 v106, v0
	s_nop 0
	v_add_f32_e32 v0, v106, v0
	v_mov_b32_e32 v106, v0
	s_nop 1
	v_permlane32_swap_b32 v106, v0
	s_and_saveexec_b64 s[26:27], s[10:11]
	v_add_f32_e32 v0, v106, v0
	ds_write_b32 v228, v0 offset:512
	s_or_b64 exec, exec, s[26:27]
	v_cvt_f32_f16_sdwa v111, v144 dst_sel:DWORD dst_unused:UNUSED_PAD src0_sel:WORD_1
	v_cvt_f32_f16_e32 v110, v144
	v_cvt_f32_f16_sdwa v107, v142 dst_sel:DWORD dst_unused:UNUSED_PAD src0_sel:WORD_1
	v_cvt_f32_f16_e32 v106, v142
	v_cvt_f32_f16_sdwa v109, v143 dst_sel:DWORD dst_unused:UNUSED_PAD src0_sel:WORD_1
	v_cvt_f32_f16_e32 v108, v143
	v_cvt_f32_f16_sdwa v113, v145 dst_sel:DWORD dst_unused:UNUSED_PAD src0_sel:WORD_1
	v_cvt_f32_f16_e32 v112, v145
	v_pk_fma_f32 v[90:91], v[90:91], v[78:79], v[110:111]
	v_add_co_u32_e32 v110, vcc, 0x30000, v210
	v_pk_fma_f32 v[96:97], v[96:97], v[72:73], v[108:109]
	v_pk_fma_f32 v[94:95], v[94:95], v[70:71], v[106:107]
	v_pk_fma_f32 v[92:93], v[92:93], v[80:81], v[112:113]
	v_addc_co_u32_e32 v111, vcc, 0, v211, vcc
	v_cvt_pk_f16_f32 v106, v94, v95
	v_cvt_pk_f16_f32 v107, v96, v97
	v_cvt_pk_f16_f32 v108, v90, v91
	v_cvt_pk_f16_f32 v109, v92, v93
	s_and_b64 vcc, exec, s[8:9]
	global_store_dwordx4 v[110:111], v[106:109], off nt
	s_cbranch_vccnz .LBB0_936
	s_nop 0
	v_pk_mul_f32 v[108:109], v[204:205], v[96:97]
	v_pk_mul_f32 v[106:107], v[200:201], v[94:95]
	v_pk_mul_f32 v[110:111], v[206:207], v[92:93]
	v_pk_mul_f32 v[112:113], v[198:199], v[90:91]
	v_cvt_pk_bf16_f32 v106, v106, v107
	v_cvt_pk_bf16_f32 v107, v108, v109
	s_nop 0
	v_cvt_pk_bf16_f32 v108, v112, v113
	v_cvt_pk_bf16_f32 v109, v110, v111
	v_add_co_u32_e32 v110, vcc, 0x30000, v208
	s_nop 1
	v_addc_co_u32_e32 v111, vcc, 0, v209, vcc
	global_store_dwordx4 v[110:111], v[106:109], off

.LBB0_938:
	v_mul_f32_e32 v0, v95, v95
	v_mul_f32_e32 v91, v91, v91
	v_mul_f32_e32 v87, v87, v87
	v_mul_f32_e32 v83, v83, v83
	v_fmac_f32_e32 v0, v94, v94
	v_mul_f32_e32 v94, v97, v97
	v_fmac_f32_e32 v91, v90, v90
	v_mul_f32_e32 v90, v93, v93
	v_fmac_f32_e32 v87, v86, v86
	v_mul_f32_e32 v86, v89, v89
	v_fmac_f32_e32 v83, v82, v82
	v_mul_f32_e32 v82, v85, v85
	v_fmac_f32_e32 v94, v96, v96
	v_fmac_f32_e32 v90, v92, v92
	v_fmac_f32_e32 v86, v88, v88
	v_fmac_f32_e32 v82, v84, v84
	v_add_f32_e32 v0, v0, v94
	v_add_f32_e32 v90, v91, v90
	v_add_f32_e32 v86, v87, v86
	v_add_f32_e32 v82, v83, v82
	v_add_f32_e32 v0, v0, v90
	v_add_f32_e32 v82, v86, v82
	s_mov_b64 s[26:27], 0xb0000
	v_add_co_u32_e32 v84, vcc, 0xb0000, v210
	v_add_f32_e32 v0, v0, v82
	v_lshl_add_u64 v[82:83], v[210:211], 0, s[26:27]
	v_addc_co_u32_e32 v85, vcc, 0, v211, vcc
	global_load_dwordx4 v[86:89], v[84:85], off
	s_nop 0
	global_load_dwordx4 v[82:85], v[82:83], off offset:256
	v_mov_b32_e32 v90, v0
	s_nop 1
	v_permlane16_swap_b32 v90, v0
	s_nop 0
	v_add_f32_e32 v0, v90, v0
	v_mov_b32_e32 v90, v0
	s_nop 1
	v_permlane32_swap_b32 v90, v0
	s_and_saveexec_b64 s[26:27], s[10:11]
	v_add_f32_e32 v0, v90, v0
	ds_write_b32 v228, v0 offset:768
	s_or_b64 exec, exec, s[26:27]
	s_waitcnt vmcnt(13)
	v_cvt_f32_f16_sdwa v95, v128 dst_sel:DWORD dst_unused:UNUSED_PAD src0_sel:WORD_1
	v_cvt_f32_f16_e32 v94, v128
	v_cvt_f32_f16_sdwa v91, v126 dst_sel:DWORD dst_unused:UNUSED_PAD src0_sel:WORD_1
	v_cvt_f32_f16_e32 v90, v126
	v_cvt_f32_f16_sdwa v93, v127 dst_sel:DWORD dst_unused:UNUSED_PAD src0_sel:WORD_1
	v_cvt_f32_f16_e32 v92, v127
	v_cvt_f32_f16_sdwa v97, v129 dst_sel:DWORD dst_unused:UNUSED_PAD src0_sel:WORD_1
	v_cvt_f32_f16_e32 v96, v129
	v_pk_fma_f32 v[58:59], v[58:59], v[78:79], v[94:95]
	v_add_co_u32_e32 v94, vcc, 0x80000, v210
	v_pk_fma_f32 v[64:65], v[64:65], v[72:73], v[92:93]
	v_pk_fma_f32 v[62:63], v[62:63], v[70:71], v[90:91]
	v_pk_fma_f32 v[60:61], v[60:61], v[80:81], v[96:97]
	v_addc_co_u32_e32 v95, vcc, 0, v211, vcc
	v_cvt_pk_f16_f32 v90, v62, v63
	v_cvt_pk_f16_f32 v91, v64, v65
	v_cvt_pk_f16_f32 v92, v58, v59
	v_cvt_pk_f16_f32 v93, v60, v61
	s_and_b64 vcc, exec, s[8:9]
	global_store_dwordx4 v[94:95], v[90:93], off nt
	s_cbranch_vccnz .LBB0_942
	s_nop 0
	v_pk_mul_f32 v[92:93], v[204:205], v[64:65]
	v_pk_mul_f32 v[90:91], v[200:201], v[62:63]
	v_pk_mul_f32 v[94:95], v[206:207], v[60:61]
	v_pk_mul_f32 v[96:97], v[198:199], v[58:59]
	v_cvt_pk_bf16_f32 v90, v90, v91
	v_cvt_pk_bf16_f32 v91, v92, v93
	s_nop 0
	v_cvt_pk_bf16_f32 v92, v96, v97
	v_cvt_pk_bf16_f32 v93, v94, v95
	v_add_co_u32_e32 v94, vcc, 0x80000, v208
	s_nop 1
	v_addc_co_u32_e32 v95, vcc, 0, v209, vcc
	global_store_dwordx4 v[94:95], v[90:93], off
